# attention steady loop: loop-edge rotation (slot rotation, counter and exit test moved in front of the closing barrier)
# baseline (speedup 1.0000x reference)
; #define WAIT_BAR(N) asm volatile("s_waitcnt vmcnt(" #N ") lgkmcnt(0)\n\ts_barrier" ::: "memory")
; #define RESC() do { if (!FIXM && resc) { asm volatile("s_waitcnt lgkmcnt(0)" ::: "memory"); \
;       _Pragma("unroll") for (int d_ = 0; d_ < 2; ++d_) _Pragma("unroll") for (int r = 0; r < 16; ++r) o[d_][r] *= wsf[crow(r, hi)]; } } while (0)
; #define ROT() do { sl_prev = sl_cur; sl_cur = sl_next; sl_next = (sl_next == (NSLOT - 1) * SLOTB) ? 0 : sl_next + SLOTB; } while (0)
; template <int THRL, bool FIXM> __device__ __forceinline__ bool attn_unit(const h16* Qrows, const h16* __restrict__ Kh, const h16* __restrict__ Vh, const int NT, h16* Yrows, const h16* BZrows, char* shm, const int tid, const float mfix, ...
;     ...
;   int t = 1;
;   for (; t + 5 < NT; t += 2) {
;     STEP(pB0, pB1, pA0, pA1, t, true, true, true);     WAIT_BAR(2); RESC(); ROT();
.LBB0_77:
	v_add_u32_e32 v0, s44, v233
	ds_read_b64_tr_b16 v[62:63], v0 offset:24576
	ds_read_b64_tr_b16 v[64:65], v0 offset:25088
	v_add_f32_e32 v51, v82, v83
	v_add_f32_e32 v51, v84, v51
	v_add_f32_e32 v51, v85, v51
	v_add_f32_e32 v51, v86, v51
	v_add_f32_e32 v51, v87, v51
	v_cvt_pk_f16_f32 v160, v82, v83
	v_cvt_pk_f16_f32 v161, v84, v85
	s_waitcnt lgkmcnt(9)
	v_mfma_f32_32x32x16_f16 v[114:129], v[192:195], v[144:147], v[2:17]
	ds_read_b64_tr_b16 v[82:83], v0 offset:28672
	ds_read_b64_tr_b16 v[84:85], v0 offset:29184
	v_add_f32_e32 v51, v88, v51
	v_add_f32_e32 v51, v89, v51
	v_add_f32_e32 v51, v90, v51
	v_add_f32_e32 v51, v91, v51
	v_cvt_pk_f16_f32 v162, v86, v87
	v_cvt_pk_f16_f32 v163, v88, v89
	s_waitcnt lgkmcnt(10)
	v_mfma_f32_32x32x16_f16 v[98:113], v[188:191], v[144:147], v[2:17]
	ds_read_b64_tr_b16 v[86:87], v0 offset:25600
	ds_read_b64_tr_b16 v[88:89], v0 offset:26112
	v_add_f32_e32 v51, v92, v51
	v_add_f32_e32 v51, v93, v51
	v_add_f32_e32 v51, v94, v51
	v_add_f32_e32 v51, v95, v51
	v_cvt_pk_f16_f32 v156, v90, v91
	v_cvt_pk_f16_f32 v157, v92, v93
	s_waitcnt lgkmcnt(11)
	v_mfma_f32_32x32x16_f16 v[114:129], v[184:187], v[140:143], v[114:129]
	ds_read_b64_tr_b16 v[90:91], v0 offset:29696
	ds_read_b64_tr_b16 v[92:93], v0 offset:30208
	v_add_f32_e32 v51, v96, v51
	v_add_f32_e32 v51, v97, v51
	v_add_f32_e32 v51, v66, v51
	v_add_f32_e32 v51, v67, v51
	v_cvt_pk_f16_f32 v158, v94, v95
	v_cvt_pk_f16_f32 v159, v96, v97
	s_waitcnt lgkmcnt(12)
	v_mfma_f32_32x32x16_f16 v[98:113], v[180:183], v[140:143], v[98:113]
	ds_read_b64_tr_b16 v[94:95], v0 offset:26624
	ds_read_b64_tr_b16 v[96:97], v0 offset:27136
	v_add_f32_e32 v51, v68, v51
	v_add_f32_e32 v51, v69, v51
	v_add_f32_e32 v51, v70, v51
	v_add_f32_e32 v51, v71, v51
	v_cvt_pk_f16_f32 v152, v66, v67
	v_cvt_pk_f16_f32 v153, v68, v69
	s_waitcnt lgkmcnt(13)
	v_mfma_f32_32x32x16_f16 v[114:129], v[176:179], v[136:139], v[114:129]
	ds_read_b64_tr_b16 v[66:67], v0 offset:30720
	ds_read_b64_tr_b16 v[68:69], v0 offset:31232
	v_add_f32_e32 v51, v72, v51
	v_add_f32_e32 v51, v73, v51
	v_add_f32_e32 v51, v74, v51
	v_add_f32_e32 v51, v75, v51
	v_cvt_pk_f16_f32 v154, v70, v71
	v_cvt_pk_f16_f32 v155, v72, v73
	s_waitcnt lgkmcnt(14)
	v_mfma_f32_32x32x16_f16 v[98:113], v[172:175], v[136:139], v[98:113]
	ds_read_b64_tr_b16 v[70:71], v0 offset:27648
	ds_read_b64_tr_b16 v[72:73], v0 offset:28160
	v_add_f32_e32 v51, v76, v51
	v_add_f32_e32 v51, v77, v51
	v_add_f32_e32 v51, v78, v51
	v_add_f32_e32 v51, v79, v51
	v_cvt_pk_f16_f32 v148, v74, v75
	v_cvt_pk_f16_f32 v149, v76, v77
	s_waitcnt lgkmcnt(14)
	v_mfma_f32_32x32x16_f16 v[114:129], v[168:171], v[132:135], v[114:129]
	ds_read_b64_tr_b16 v[74:75], v0 offset:31744
	ds_read_b64_tr_b16 v[76:77], v0 offset:32256
	v_add_f32_e32 v0, v80, v51
	v_add_f32_e32 v0, v81, v0
	v_add_f32_e32 v0, 0, v0
	v_cvt_pk_f16_f32 v150, v78, v79
	v_cvt_pk_f16_f32 v151, v80, v81
	v_mfma_f32_32x32x16_f16 v[98:113], v[164:167], v[132:135], v[98:113]
	v_add_f32_e32 v0, v50, v0
	s_add_i32 s43, s42, s97
	s_mov_b32 s44, m0
	s_mov_b32 m0, s43
	s_nop 0
	global_load_lds_dwordx4 v214, s[100:101]
	s_mov_b32 m0, s44
	s_add_i32 s43, s25, s83
	s_mov_b32 s44, m0
	s_mov_b32 m0, s43
	s_nop 0
	global_load_lds_dwordx4 v208, vcc
	s_mov_b32 m0, s44
	s_add_u32 s100, s100, 0x2000
	s_addc_u32 s101, s101, 0
	s_add_u32 vcc_lo, vcc_lo, 0x2000
	s_addc_u32 vcc_hi, vcc_hi, 0
	s_waitcnt lgkmcnt(14)
	v_mfma_f32_32x32x16_f16 v[18:33], v[160:163], v[62:65], v[18:33]
	v_exp_f32_e32 v114, v114
	v_exp_f32_e32 v115, v115
	v_exp_f32_e32 v116, v116
	v_exp_f32_e32 v117, v117
	s_waitcnt lgkmcnt(12)
	v_mfma_f32_32x32x16_f16 v[34:49], v[160:163], v[82:85], v[34:49]
	v_exp_f32_e32 v118, v118
	v_exp_f32_e32 v119, v119
	v_exp_f32_e32 v120, v120
	v_exp_f32_e32 v121, v121
	v_add_u32_e32 v50, s25, v219
	ds_read_b128 v[62:65], v50
	ds_read_b128 v[164:167], v50 offset:512
	s_waitcnt lgkmcnt(12)
	v_mfma_f32_32x32x16_f16 v[18:33], v[156:159], v[86:89], v[18:33]
	v_exp_f32_e32 v122, v122
	v_exp_f32_e32 v123, v123
	v_exp_f32_e32 v124, v124
	v_exp_f32_e32 v125, v125
	ds_read_b128 v[168:171], v50 offset:2048
	ds_read_b128 v[172:175], v50 offset:2560
	s_waitcnt lgkmcnt(12)
	v_mfma_f32_32x32x16_f16 v[34:49], v[156:159], v[90:93], v[34:49]
	v_exp_f32_e32 v126, v126
	v_exp_f32_e32 v127, v127
	v_exp_f32_e32 v128, v128
	v_exp_f32_e32 v129, v129
	ds_read_b128 v[176:179], v50 offset:4096
	ds_read_b128 v[180:183], v50 offset:4608
	s_waitcnt lgkmcnt(12)
	v_mfma_f32_32x32x16_f16 v[18:33], v[152:155], v[94:97], v[18:33]
	v_exp_f32_e32 v98, v98
	v_exp_f32_e32 v99, v99
	v_exp_f32_e32 v100, v100
	v_exp_f32_e32 v101, v101
	ds_read_b128 v[184:187], v50 offset:6144
	ds_read_b128 v[50:53], v50 offset:6656
	s_waitcnt lgkmcnt(12)
	v_mfma_f32_32x32x16_f16 v[34:49], v[152:155], v[66:69], v[34:49]
	v_exp_f32_e32 v102, v102
	v_exp_f32_e32 v103, v103
	v_exp_f32_e32 v104, v104
	v_exp_f32_e32 v105, v105
	s_waitcnt lgkmcnt(10)
	v_mfma_f32_32x32x16_f16 v[18:33], v[148:151], v[70:73], v[18:33]
	v_exp_f32_e32 v106, v106
	v_exp_f32_e32 v107, v107
	v_exp_f32_e32 v108, v108
	v_exp_f32_e32 v109, v109
	s_waitcnt lgkmcnt(8)
	v_mfma_f32_32x32x16_f16 v[34:49], v[148:151], v[74:77], v[34:49]
	v_exp_f32_e32 v110, v110
	v_exp_f32_e32 v111, v111
	v_exp_f32_e32 v112, v112
	v_exp_f32_e32 v113, v113
	s_waitcnt vmcnt(2) lgkmcnt(8)
	s_barrier
; #define WAIT_BAR(N) asm volatile("s_waitcnt vmcnt(" #N ") lgkmcnt(0)\n\ts_barrier" ::: "memory")
; #define RESC() do { if (!FIXM && resc) { asm volatile("s_waitcnt lgkmcnt(0)" ::: "memory"); \
;       _Pragma("unroll") for (int d_ = 0; d_ < 2; ++d_) _Pragma("unroll") for (int r = 0; r < 16; ++r) o[d_][r] *= wsf[crow(r, hi)]; } } while (0)
; #define ROT() do { sl_prev = sl_cur; sl_cur = sl_next; sl_next = (sl_next == (NSLOT - 1) * SLOTB) ? 0 : sl_next + SLOTB; } while (0)
; template <int THRL, bool FIXM> __device__ __forceinline__ bool attn_unit(const h16* Qrows, const h16* __restrict__ Kh, const h16* __restrict__ Vh, const int NT, h16* Yrows, const h16* BZrows, char* shm, const int tid, const float mfix, ...
;     ...
;   int t = 1;
;   for (; t + 5 < NT; t += 2) {
;     STEP(pB0, pB1, pA0, pA1, t, true, true, true);     WAIT_BAR(2); RESC(); ROT();
;     STEP(pA0, pA1, pB0, pB1, t + 1, true, true, true); WAIT_BAR(2); RESC(); ROT();
;   }
	s_add_i32 s43, s25, 0x2000
	s_cmpk_lg_i32 s25, 0x4000
	s_cselect_b32 s43, s43, 0
	v_add_u32_e32 v192, s42, v233
	ds_read_b64_tr_b16 v[188:189], v192 offset:24576
	ds_read_b64_tr_b16 v[190:191], v192 offset:25088
	s_waitcnt lgkmcnt(9)
	v_mfma_f32_32x32x16_f16 v[82:97], v[62:65], v[144:147], v[2:17]
	v_add_f32_e32 v66, v114, v115
	v_add_f32_e32 v66, v116, v66
	v_add_f32_e32 v66, v117, v66
	v_add_f32_e32 v66, v118, v66
	v_add_f32_e32 v66, v119, v66
	v_cvt_pk_f16_f32 v160, v114, v115
	v_cvt_pk_f16_f32 v161, v116, v117
	ds_read_b64_tr_b16 v[62:63], v192 offset:28672
	ds_read_b64_tr_b16 v[64:65], v192 offset:29184
	v_add_f32_e32 v66, v120, v66
	v_add_f32_e32 v66, v121, v66
	v_add_f32_e32 v66, v122, v66
	v_add_f32_e32 v148, v123, v66
	s_waitcnt lgkmcnt(10)
	v_mfma_f32_32x32x16_f16 v[66:81], v[164:167], v[144:147], v[2:17]
	v_cvt_pk_f16_f32 v162, v118, v119
	v_cvt_pk_f16_f32 v163, v120, v121
	ds_read_b64_tr_b16 v[114:115], v192 offset:25600
	ds_read_b64_tr_b16 v[116:117], v192 offset:26112
	s_waitcnt lgkmcnt(11)
	v_mfma_f32_32x32x16_f16 v[82:97], v[168:171], v[140:143], v[82:97]
	v_add_f32_e32 v118, v124, v148
	v_add_f32_e32 v118, v125, v118
	v_add_f32_e32 v118, v126, v118
	v_add_f32_e32 v148, v127, v118
	v_cvt_pk_f16_f32 v156, v122, v123
	v_cvt_pk_f16_f32 v157, v124, v125
	ds_read_b64_tr_b16 v[118:119], v192 offset:29696
	ds_read_b64_tr_b16 v[120:121], v192 offset:30208
	s_waitcnt lgkmcnt(12)
	v_mfma_f32_32x32x16_f16 v[66:81], v[172:175], v[140:143], v[66:81]
	v_add_f32_e32 v122, v128, v148
	v_add_f32_e32 v122, v129, v122
	v_add_f32_e32 v122, v98, v122
	v_add_f32_e32 v148, v99, v122
	v_cvt_pk_f16_f32 v158, v126, v127
	v_cvt_pk_f16_f32 v159, v128, v129
	ds_read_b64_tr_b16 v[122:123], v192 offset:26624
	ds_read_b64_tr_b16 v[124:125], v192 offset:27136
	s_waitcnt lgkmcnt(13)
	v_mfma_f32_32x32x16_f16 v[82:97], v[176:179], v[136:139], v[82:97]
	v_add_f32_e32 v126, v100, v148
	v_add_f32_e32 v126, v101, v126
	v_add_f32_e32 v126, v102, v126
	v_add_f32_e32 v126, v103, v126
	v_cvt_pk_f16_f32 v152, v98, v99
	v_cvt_pk_f16_f32 v153, v100, v101
	ds_read_b64_tr_b16 v[98:99], v192 offset:30720
	ds_read_b64_tr_b16 v[100:101], v192 offset:31232
	s_waitcnt lgkmcnt(14)
	v_mfma_f32_32x32x16_f16 v[66:81], v[180:183], v[136:139], v[66:81]
	v_add_f32_e32 v126, v104, v126
	v_add_f32_e32 v126, v105, v126
	v_add_f32_e32 v126, v106, v126
	v_add_f32_e32 v126, v107, v126
	v_cvt_pk_f16_f32 v154, v102, v103
	v_cvt_pk_f16_f32 v155, v104, v105
	ds_read_b64_tr_b16 v[102:103], v192 offset:27648
	ds_read_b64_tr_b16 v[104:105], v192 offset:28160
	s_waitcnt lgkmcnt(14)
	v_mfma_f32_32x32x16_f16 v[82:97], v[184:187], v[132:135], v[82:97]
	v_add_f32_e32 v126, v108, v126
	v_add_f32_e32 v126, v109, v126
	v_add_f32_e32 v126, v110, v126
	v_add_f32_e32 v126, v111, v126
	v_cvt_pk_f16_f32 v148, v106, v107
	v_cvt_pk_f16_f32 v149, v108, v109
	ds_read_b64_tr_b16 v[106:107], v192 offset:31744
	ds_read_b64_tr_b16 v[108:109], v192 offset:32256
	v_mfma_f32_32x32x16_f16 v[66:81], v[50:53], v[132:135], v[66:81]
	v_add_f32_e32 v50, v112, v126
	v_add_f32_e32 v50, v113, v50
	v_add_f32_e32 v50, 0, v50
	v_cvt_pk_f16_f32 v150, v110, v111
	v_cvt_pk_f16_f32 v151, v112, v113
	s_add_i32 s42, s25, s97
	s_mov_b32 s44, m0
	s_mov_b32 m0, s42
	s_nop 0
	global_load_lds_dwordx4 v214, s[100:101]
	s_mov_b32 m0, s44
	s_add_i32 s42, s43, s83
	s_mov_b32 s44, m0
	s_mov_b32 m0, s42
	s_nop 0
	global_load_lds_dwordx4 v208, vcc
	s_mov_b32 m0, s44
	s_add_u32 s100, s100, 0x2000
	s_addc_u32 s101, s101, 0
	s_add_u32 vcc_lo, vcc_lo, 0x2000
	s_addc_u32 vcc_hi, vcc_hi, 0
	v_add_f32_e32 v50, v0, v50
	s_waitcnt lgkmcnt(14)
	v_mfma_f32_32x32x16_f16 v[18:33], v[160:163], v[188:191], v[18:33]
	v_exp_f32_e32 v82, v82
	v_exp_f32_e32 v83, v83
	v_exp_f32_e32 v84, v84
	v_exp_f32_e32 v85, v85
	s_waitcnt lgkmcnt(12)
	v_mfma_f32_32x32x16_f16 v[34:49], v[160:163], v[62:65], v[34:49]
	v_exp_f32_e32 v86, v86
	v_exp_f32_e32 v87, v87
	v_exp_f32_e32 v88, v88
	v_exp_f32_e32 v89, v89
	v_add_u32_e32 v0, s43, v219
	ds_read_b128 v[192:195], v0
	ds_read_b128 v[188:191], v0 offset:512
	s_waitcnt lgkmcnt(12)
	v_mfma_f32_32x32x16_f16 v[18:33], v[156:159], v[114:117], v[18:33]
	v_exp_f32_e32 v90, v90
	v_exp_f32_e32 v91, v91
	v_exp_f32_e32 v92, v92
	v_exp_f32_e32 v93, v93
	ds_read_b128 v[184:187], v0 offset:2048
	ds_read_b128 v[180:183], v0 offset:2560
	s_waitcnt lgkmcnt(12)
	v_mfma_f32_32x32x16_f16 v[34:49], v[156:159], v[118:121], v[34:49]
	v_exp_f32_e32 v94, v94
	v_exp_f32_e32 v95, v95
	v_exp_f32_e32 v96, v96
	v_exp_f32_e32 v97, v97
	ds_read_b128 v[176:179], v0 offset:4096
	ds_read_b128 v[172:175], v0 offset:4608
	s_waitcnt lgkmcnt(12)
	v_mfma_f32_32x32x16_f16 v[18:33], v[152:155], v[122:125], v[18:33]
	v_exp_f32_e32 v66, v66
	v_exp_f32_e32 v67, v67
	v_exp_f32_e32 v68, v68
	v_exp_f32_e32 v69, v69
	ds_read_b128 v[168:171], v0 offset:6144
	ds_read_b128 v[164:167], v0 offset:6656
	s_waitcnt lgkmcnt(12)
	v_mfma_f32_32x32x16_f16 v[34:49], v[152:155], v[98:101], v[34:49]
	v_exp_f32_e32 v70, v70
	v_exp_f32_e32 v71, v71
	v_exp_f32_e32 v72, v72
	v_exp_f32_e32 v73, v73
	s_waitcnt lgkmcnt(10)
	v_mfma_f32_32x32x16_f16 v[18:33], v[148:151], v[102:105], v[18:33]
	v_exp_f32_e32 v74, v74
	v_exp_f32_e32 v75, v75
	v_exp_f32_e32 v76, v76
	v_exp_f32_e32 v77, v77
	s_waitcnt lgkmcnt(8)
	v_mfma_f32_32x32x16_f16 v[34:49], v[148:151], v[106:109], v[34:49]
	v_exp_f32_e32 v78, v78
	v_exp_f32_e32 v79, v79
	v_exp_f32_e32 v80, v80
	v_exp_f32_e32 v81, v81
	s_add_i32 s45, s43, 0x2000
	s_cmpk_lg_i32 s43, 0x4000
	s_mov_b32 s44, s25
	s_cselect_b32 s25, s45, 0
	s_add_i32 s24, s24, 2
	v_lshl_add_u64 v[54:55], v[54:55], 0, s[62:63]
	v_lshl_add_u64 v[56:57], v[56:57], 0, s[62:63]
	s_mov_b32 s42, s43
	s_cmp_lt_u32 s24, 29
	s_waitcnt vmcnt(2) lgkmcnt(8)
	s_barrier
	s_cbranch_scc1 .LBB0_77
	s_mov_b64 s[36:37], 0x10c84000
	s_mov_b64 s[60:61], 0x10388000
	s_mov_b32 s45, 31
	s_branch .LBB0_80
